# conv remnant phase: hand-written sample-row conv (one 8-row sequence x 8 columns per thread, waves 4-6), boundary items two per thread on waves 0-2, compiled conv loop removed
# speedup vs baseline: 1.0525x; 1.0038x over previous
.LBB0_182:
	s_mul_i32 s2, s84, 0x160
	v_add_u32_e32 v0, s2, v241
	s_movk_i32 s2, 0xb0
	v_cmp_gt_u32_e32 vcc, s2, v241
	s_and_saveexec_b64 s[4:5], vcc
	s_cbranch_execz .Lbnd_done
	s_mov_b32 s20, 0
.Lbnd_loop:
	s_load_dwordx4 s[8:11], s[54:55], 0xb8
	v_readlane_b32 s14, v253, 41
	s_add_u32 s6, s82, 0xd200000
	s_addc_u32 s7, s83, 0
	s_add_u32 s12, s6, 0x6000000
	s_addc_u32 s13, s7, 0
	v_lshrrev_b32_e32 v2, 5, v0
	s_mov_b32 s2, 0xba2e8ba3
	v_mul_hi_u32 v2, v2, s2
	v_lshrrev_b32_e32 v2, 3, v2
	v_mul_u32_u24_e32 v3, 0x160, v2
	v_sub_u32_e32 v3, v0, v3
	v_lshlrev_b32_e32 v6, 4, v3
	v_lshlrev_b32_e32 v7, 5, v3
	s_mul_i32 s15, s14, 0x10800
	s_mul_i32 s14, s14, 0x5800
	s_waitcnt lgkmcnt(0)
	s_add_u32 s8, s8, s15
	s_addc_u32 s9, s9, 0
	s_add_u32 s10, s10, s14
	s_addc_u32 s11, s11, 0
	global_load_dwordx4 v[16:19], v7, s[8:9] offset:0
	global_load_dwordx4 v[20:23], v7, s[8:9] offset:16
	v_add_u32_e32 v8, 0x2c00, v7
	global_load_dwordx4 v[48:51], v8, s[8:9]
	v_add_u32_e32 v8, 0x2c10, v7
	global_load_dwordx4 v[52:55], v8, s[8:9]
	v_add_u32_e32 v8, 0x5800, v7
	global_load_dwordx4 v[24:27], v8, s[8:9]
	v_add_u32_e32 v8, 0x5810, v7
	global_load_dwordx4 v[28:31], v8, s[8:9]
	v_add_u32_e32 v8, 0x8400, v7
	global_load_dwordx4 v[56:59], v8, s[8:9]
	v_add_u32_e32 v8, 0x8410, v7
	global_load_dwordx4 v[60:63], v8, s[8:9]
	v_add_u32_e32 v8, 0xb000, v7
	global_load_dwordx4 v[32:35], v8, s[8:9]
	v_add_u32_e32 v8, 0xb010, v7
	global_load_dwordx4 v[36:39], v8, s[8:9]
	v_add_u32_e32 v8, 0xdc00, v7
	global_load_dwordx4 v[64:67], v8, s[8:9]
	v_add_u32_e32 v8, 0xdc10, v7
	global_load_dwordx4 v[68:71], v8, s[8:9]
	global_load_dwordx4 v[40:43], v7, s[10:11] offset:0
	global_load_dwordx4 v[44:47], v7, s[10:11] offset:16
	v_add_u32_e32 v8, 0x2c00, v7
	global_load_dwordx4 v[72:75], v8, s[10:11]
	v_add_u32_e32 v8, 0x2c10, v7
	global_load_dwordx4 v[76:79], v8, s[10:11]
	v_lshlrev_b32_e32 v9, 2, v2
	v_mov_b64_e32 v[10:11], s[12:13]
	v_mad_u64_u32 v[10:11], s[2:3], v9, s91, v[10:11]
	v_mov_b32_e32 v12, v6
	v_mov_b32_e32 v13, 0
	v_lshl_add_u64 v[10:11], v[10:11], 0, v[12:13]
	v_mov_b32_e32 v80, 0
	v_mov_b32_e32 v81, 0
	v_mov_b32_e32 v82, 0
	v_mov_b32_e32 v83, 0
	v_mov_b32_e32 v84, 0
	v_mov_b32_e32 v85, 0
	v_mov_b32_e32 v86, 0
	v_mov_b32_e32 v87, 0
	v_mov_b32_e32 v96, 0
	v_mov_b32_e32 v97, 0
	v_mov_b32_e32 v98, 0
	v_mov_b32_e32 v99, 0
	v_mov_b32_e32 v100, 0
	v_mov_b32_e32 v101, 0
	v_mov_b32_e32 v102, 0
	v_mov_b32_e32 v103, 0
	global_load_dwordx4 v[88:91], v[10:11], off
	s_mov_b64 s[2:3], 0x1600
	v_lshl_add_u64 v[12:13], v[10:11], 0, s[2:3]
	global_load_dwordx4 v[104:107], v[12:13], off
	s_mov_b64 s[2:3], 0x2c00
	v_lshl_add_u64 v[14:15], v[10:11], 0, s[2:3]
	global_load_dwordx4 v[92:95], v[14:15], off
	s_mov_b64 s[2:3], 0x4200
	v_lshl_add_u64 v[14:15], v[10:11], 0, s[2:3]
	global_load_dwordx4 v[108:111], v[14:15], off
	v_and_b32_e32 v9, 0x7f, v2
	v_cmp_ne_u32_e32 vcc, 0, v9
	s_and_saveexec_b64 s[16:17], vcc
	s_mov_b64 s[2:3], 0x2c00
	v_mov_b32_e32 v14, v10
	v_mov_b32_e32 v15, v11
	v_subrev_co_u32_e32 v14, vcc, 0x2c00, v10
	v_subbrev_co_u32_e32 v15, vcc, 0, v11, vcc
	global_load_dwordx4 v[84:87], v[14:15], off
	s_mov_b64 s[2:3], 0x1600
	v_lshl_add_u64 v[12:13], v[14:15], 0, s[2:3]
	global_load_dwordx4 v[100:103], v[12:13], off
	v_subrev_co_u32_e32 v14, vcc, 0x5800, v10
	v_subbrev_co_u32_e32 v15, vcc, 0, v11, vcc
	global_load_dwordx4 v[80:83], v[14:15], off
	v_lshl_add_u64 v[12:13], v[14:15], 0, s[2:3]
	global_load_dwordx4 v[96:99], v[12:13], off
	s_or_b64 exec, exec, s[16:17]
	s_waitcnt vmcnt(0)
	v_lshlrev_b32_e32 v112, 16, v80
	v_and_b32_e32 v113, 0xffff0000, v80
	v_lshlrev_b32_e32 v114, 16, v81
	v_and_b32_e32 v115, 0xffff0000, v81
	v_lshlrev_b32_e32 v116, 16, v82
	v_and_b32_e32 v117, 0xffff0000, v82
	v_lshlrev_b32_e32 v118, 16, v83
	v_and_b32_e32 v119, 0xffff0000, v83
	v_lshlrev_b32_e32 v120, 16, v84
	v_and_b32_e32 v121, 0xffff0000, v84
	v_lshlrev_b32_e32 v122, 16, v85
	v_and_b32_e32 v123, 0xffff0000, v85
	v_lshlrev_b32_e32 v124, 16, v86
	v_and_b32_e32 v125, 0xffff0000, v86
	v_lshlrev_b32_e32 v126, 16, v87
	v_and_b32_e32 v127, 0xffff0000, v87
	v_lshlrev_b32_e32 v128, 16, v88
	v_and_b32_e32 v129, 0xffff0000, v88
	v_lshlrev_b32_e32 v130, 16, v89
	v_and_b32_e32 v131, 0xffff0000, v89
	v_lshlrev_b32_e32 v132, 16, v90
	v_and_b32_e32 v133, 0xffff0000, v90
	v_lshlrev_b32_e32 v134, 16, v91
	v_and_b32_e32 v135, 0xffff0000, v91
	v_lshlrev_b32_e32 v136, 16, v92
	v_and_b32_e32 v137, 0xffff0000, v92
	v_lshlrev_b32_e32 v138, 16, v93
	v_and_b32_e32 v139, 0xffff0000, v93
	v_lshlrev_b32_e32 v140, 16, v94
	v_and_b32_e32 v141, 0xffff0000, v94
	v_lshlrev_b32_e32 v142, 16, v95
	v_and_b32_e32 v143, 0xffff0000, v95
	v_lshlrev_b32_e32 v144, 16, v96
	v_and_b32_e32 v145, 0xffff0000, v96
	v_lshlrev_b32_e32 v146, 16, v97
	v_and_b32_e32 v147, 0xffff0000, v97
	v_lshlrev_b32_e32 v148, 16, v98
	v_and_b32_e32 v149, 0xffff0000, v98
	v_lshlrev_b32_e32 v150, 16, v99
	v_and_b32_e32 v151, 0xffff0000, v99
	v_lshlrev_b32_e32 v152, 16, v100
	v_and_b32_e32 v153, 0xffff0000, v100
	v_lshlrev_b32_e32 v154, 16, v101
	v_and_b32_e32 v155, 0xffff0000, v101
	v_lshlrev_b32_e32 v156, 16, v102
	v_and_b32_e32 v157, 0xffff0000, v102
	v_lshlrev_b32_e32 v158, 16, v103
	v_and_b32_e32 v159, 0xffff0000, v103
	v_lshlrev_b32_e32 v160, 16, v104
	v_and_b32_e32 v161, 0xffff0000, v104
	v_lshlrev_b32_e32 v162, 16, v105
	v_and_b32_e32 v163, 0xffff0000, v105
	v_lshlrev_b32_e32 v164, 16, v106
	v_and_b32_e32 v165, 0xffff0000, v106
	v_lshlrev_b32_e32 v166, 16, v107
	v_and_b32_e32 v167, 0xffff0000, v107
	v_lshlrev_b32_e32 v168, 16, v108
	v_and_b32_e32 v169, 0xffff0000, v108
	v_lshlrev_b32_e32 v170, 16, v109
	v_and_b32_e32 v171, 0xffff0000, v109
	v_lshlrev_b32_e32 v172, 16, v110
	v_and_b32_e32 v173, 0xffff0000, v110
	v_lshlrev_b32_e32 v174, 16, v111
	v_and_b32_e32 v175, 0xffff0000, v111
	v_pk_fma_f32 v[176:177], v[112:113], v[16:17], v[40:41]
	v_pk_fma_f32 v[176:177], v[120:121], v[24:25], v[176:177]
	v_pk_fma_f32 v[176:177], v[128:129], v[32:33], v[176:177]
	v_pk_fma_f32 v[184:185], v[120:121], v[16:17], v[40:41]
	v_pk_fma_f32 v[184:185], v[128:129], v[24:25], v[184:185]
	v_pk_fma_f32 v[184:185], v[136:137], v[32:33], v[184:185]
	v_pk_fma_f32 v[178:179], v[114:115], v[18:19], v[42:43]
	v_pk_fma_f32 v[178:179], v[122:123], v[26:27], v[178:179]
	v_pk_fma_f32 v[178:179], v[130:131], v[34:35], v[178:179]
	v_pk_fma_f32 v[186:187], v[122:123], v[18:19], v[42:43]
	v_pk_fma_f32 v[186:187], v[130:131], v[26:27], v[186:187]
	v_pk_fma_f32 v[186:187], v[138:139], v[34:35], v[186:187]
	v_pk_fma_f32 v[180:181], v[116:117], v[20:21], v[44:45]
	v_pk_fma_f32 v[180:181], v[124:125], v[28:29], v[180:181]
	v_pk_fma_f32 v[180:181], v[132:133], v[36:37], v[180:181]
	v_pk_fma_f32 v[188:189], v[124:125], v[20:21], v[44:45]
	v_pk_fma_f32 v[188:189], v[132:133], v[28:29], v[188:189]
	v_pk_fma_f32 v[188:189], v[140:141], v[36:37], v[188:189]
	v_pk_fma_f32 v[182:183], v[118:119], v[22:23], v[46:47]
	v_pk_fma_f32 v[182:183], v[126:127], v[30:31], v[182:183]
	v_pk_fma_f32 v[182:183], v[134:135], v[38:39], v[182:183]
	v_pk_fma_f32 v[190:191], v[126:127], v[22:23], v[46:47]
	v_pk_fma_f32 v[190:191], v[134:135], v[30:31], v[190:191]
	v_pk_fma_f32 v[190:191], v[142:143], v[38:39], v[190:191]
	v_pk_fma_f32 v[192:193], v[144:145], v[48:49], v[72:73]
	v_pk_fma_f32 v[192:193], v[152:153], v[56:57], v[192:193]
	v_pk_fma_f32 v[192:193], v[160:161], v[64:65], v[192:193]
	v_pk_fma_f32 v[200:201], v[152:153], v[48:49], v[72:73]
	v_pk_fma_f32 v[200:201], v[160:161], v[56:57], v[200:201]
	v_pk_fma_f32 v[200:201], v[168:169], v[64:65], v[200:201]
	v_pk_fma_f32 v[194:195], v[146:147], v[50:51], v[74:75]
	v_pk_fma_f32 v[194:195], v[154:155], v[58:59], v[194:195]
	v_pk_fma_f32 v[194:195], v[162:163], v[66:67], v[194:195]
	v_pk_fma_f32 v[202:203], v[154:155], v[50:51], v[74:75]
	v_pk_fma_f32 v[202:203], v[162:163], v[58:59], v[202:203]
	v_pk_fma_f32 v[202:203], v[170:171], v[66:67], v[202:203]
	v_pk_fma_f32 v[196:197], v[148:149], v[52:53], v[76:77]
	v_pk_fma_f32 v[196:197], v[156:157], v[60:61], v[196:197]
	v_pk_fma_f32 v[196:197], v[164:165], v[68:69], v[196:197]
	v_pk_fma_f32 v[204:205], v[156:157], v[52:53], v[76:77]
	v_pk_fma_f32 v[204:205], v[164:165], v[60:61], v[204:205]
	v_pk_fma_f32 v[204:205], v[172:173], v[68:69], v[204:205]
	v_pk_fma_f32 v[198:199], v[150:151], v[54:55], v[78:79]
	v_pk_fma_f32 v[198:199], v[158:159], v[62:63], v[198:199]
	v_pk_fma_f32 v[198:199], v[166:167], v[70:71], v[198:199]
	v_pk_fma_f32 v[206:207], v[158:159], v[54:55], v[78:79]
	v_pk_fma_f32 v[206:207], v[166:167], v[62:63], v[206:207]
	v_pk_fma_f32 v[206:207], v[174:175], v[70:71], v[206:207]
	s_mov_b32 s2, 0xbfb8aa3b
	s_mov_b32 s3, 0xbfb8aa3b
	v_pk_mul_f32 v[216:217], v[176:177], s[2:3]
	v_exp_f32_e32 v216, v216
	v_exp_f32_e32 v217, v217
	s_nop 0
	v_pk_add_f32 v[216:217], v[216:217], 1.0 op_sel_hi:[1,0]
	v_rcp_f32_e32 v216, v216
	v_rcp_f32_e32 v217, v217
	s_nop 0
	v_pk_mul_f32 v[216:217], v[216:217], v[176:177]
	v_pk_mul_f32 v[216:217], v[216:217], v[192:193]
	v_cvt_pk_bf16_f32 v208, v216, v217
	v_pk_mul_f32 v[216:217], v[178:179], s[2:3]
	v_exp_f32_e32 v216, v216
	v_exp_f32_e32 v217, v217
	s_nop 0
	v_pk_add_f32 v[216:217], v[216:217], 1.0 op_sel_hi:[1,0]
	v_rcp_f32_e32 v216, v216
	v_rcp_f32_e32 v217, v217
	s_nop 0
	v_pk_mul_f32 v[216:217], v[216:217], v[178:179]
	v_pk_mul_f32 v[216:217], v[216:217], v[194:195]
	v_cvt_pk_bf16_f32 v209, v216, v217
	v_pk_mul_f32 v[216:217], v[180:181], s[2:3]
	v_exp_f32_e32 v216, v216
	v_exp_f32_e32 v217, v217
	s_nop 0
	v_pk_add_f32 v[216:217], v[216:217], 1.0 op_sel_hi:[1,0]
	v_rcp_f32_e32 v216, v216
	v_rcp_f32_e32 v217, v217
	s_nop 0
	v_pk_mul_f32 v[216:217], v[216:217], v[180:181]
	v_pk_mul_f32 v[216:217], v[216:217], v[196:197]
	v_cvt_pk_bf16_f32 v210, v216, v217
	v_pk_mul_f32 v[216:217], v[182:183], s[2:3]
	v_exp_f32_e32 v216, v216
	v_exp_f32_e32 v217, v217
	s_nop 0
	v_pk_add_f32 v[216:217], v[216:217], 1.0 op_sel_hi:[1,0]
	v_rcp_f32_e32 v216, v216
	v_rcp_f32_e32 v217, v217
	s_nop 0
	v_pk_mul_f32 v[216:217], v[216:217], v[182:183]
	v_pk_mul_f32 v[216:217], v[216:217], v[198:199]
	v_cvt_pk_bf16_f32 v211, v216, v217
	v_pk_mul_f32 v[216:217], v[184:185], s[2:3]
	v_exp_f32_e32 v216, v216
	v_exp_f32_e32 v217, v217
	s_nop 0
	v_pk_add_f32 v[216:217], v[216:217], 1.0 op_sel_hi:[1,0]
	v_rcp_f32_e32 v216, v216
	v_rcp_f32_e32 v217, v217
	s_nop 0
	v_pk_mul_f32 v[216:217], v[216:217], v[184:185]
	v_pk_mul_f32 v[216:217], v[216:217], v[200:201]
	v_cvt_pk_bf16_f32 v212, v216, v217
	v_pk_mul_f32 v[216:217], v[186:187], s[2:3]
	v_exp_f32_e32 v216, v216
	v_exp_f32_e32 v217, v217
	s_nop 0
	v_pk_add_f32 v[216:217], v[216:217], 1.0 op_sel_hi:[1,0]
	v_rcp_f32_e32 v216, v216
	v_rcp_f32_e32 v217, v217
	s_nop 0
	v_pk_mul_f32 v[216:217], v[216:217], v[186:187]
	v_pk_mul_f32 v[216:217], v[216:217], v[202:203]
	v_cvt_pk_bf16_f32 v213, v216, v217
	v_pk_mul_f32 v[216:217], v[188:189], s[2:3]
	v_exp_f32_e32 v216, v216
	v_exp_f32_e32 v217, v217
	s_nop 0
	v_pk_add_f32 v[216:217], v[216:217], 1.0 op_sel_hi:[1,0]
	v_rcp_f32_e32 v216, v216
	v_rcp_f32_e32 v217, v217
	s_nop 0
	v_pk_mul_f32 v[216:217], v[216:217], v[188:189]
	v_pk_mul_f32 v[216:217], v[216:217], v[204:205]
	v_cvt_pk_bf16_f32 v214, v216, v217
	v_pk_mul_f32 v[216:217], v[190:191], s[2:3]
	v_exp_f32_e32 v216, v216
	v_exp_f32_e32 v217, v217
	s_nop 0
	v_pk_add_f32 v[216:217], v[216:217], 1.0 op_sel_hi:[1,0]
	v_rcp_f32_e32 v216, v216
	v_rcp_f32_e32 v217, v217
	s_nop 0
	v_pk_mul_f32 v[216:217], v[216:217], v[190:191]
	v_pk_mul_f32 v[216:217], v[216:217], v[206:207]
	v_cvt_pk_bf16_f32 v215, v216, v217
	v_lshlrev_b32_e32 v9, 6, v2
	v_mov_b64_e32 v[10:11], s[6:7]
	s_movk_i32 s2, 0x1600
	v_mad_u64_u32 v[10:11], s[16:17], v9, s2, v[10:11]
	v_mov_b32_e32 v12, v6
	v_mov_b32_e32 v13, 0
	v_lshl_add_u64 v[10:11], v[10:11], 0, v[12:13]
	global_store_dwordx4 v[10:11], v[208:211], off
	s_mov_b64 s[2:3], 0x1600
	v_lshl_add_u64 v[10:11], v[10:11], 0, s[2:3]
	global_store_dwordx4 v[10:11], v[212:215], off
	v_add_u32_e32 v0, 0xb0, v0
	s_add_i32 s20, s20, 1
	s_cmp_lt_u32 s20, 2
	s_cbranch_scc1 .Lbnd_loop
.Lbnd_done:
	s_or_b64 exec, exec, s[4:5]
	v_subrev_u32_e32 v0, 0x100, v241
	s_movk_i32 s2, 0xb0
	v_cmp_gt_u32_e32 vcc, s2, v0
	s_and_saveexec_b64 s[4:5], vcc
	s_cbranch_execz .LBB0_193
	s_load_dwordx4 s[8:11], s[54:55], 0xb8
	s_load_dwordx2 s[12:13], s[54:55], 0x30
	v_readlane_b32 s14, v253, 41
	s_add_u32 s6, s82, 0xd200000
	s_addc_u32 s7, s83, 0
	s_mul_i32 s2, s84, 0xb0
	v_add_u32_e32 v0, s2, v0
	v_lshrrev_b32_e32 v2, 5, v0
	s_mov_b32 s2, 0xba2e8ba3
	v_mul_hi_u32 v2, v2, s2
	v_lshrrev_b32_e32 v2, 3, v2
	v_mul_u32_u24_e32 v3, 0x160, v2
	v_sub_u32_e32 v3, v0, v3
	v_lshlrev_b32_e32 v6, 4, v3
	v_lshlrev_b32_e32 v7, 5, v3
	s_mul_i32 s15, s14, 0x10800
	s_mul_i32 s16, s14, 0x5800
	s_mul_i32 s17, s14, 0x580000
	s_waitcnt lgkmcnt(0)
	s_add_u32 s8, s8, s15
	s_addc_u32 s9, s9, 0
	s_add_u32 s10, s10, s16
	s_addc_u32 s11, s11, 0
	s_add_u32 s12, s12, s17
	s_addc_u32 s13, s13, 0
	global_load_dwordx4 v[16:19], v7, s[8:9] offset:0
	global_load_dwordx4 v[20:23], v7, s[8:9] offset:16
	v_add_u32_e32 v8, 0x2c00, v7
	global_load_dwordx4 v[48:51], v8, s[8:9]
	v_add_u32_e32 v8, 0x2c10, v7
	global_load_dwordx4 v[52:55], v8, s[8:9]
	v_add_u32_e32 v8, 0x5800, v7
	global_load_dwordx4 v[24:27], v8, s[8:9]
	v_add_u32_e32 v8, 0x5810, v7
	global_load_dwordx4 v[28:31], v8, s[8:9]
	v_add_u32_e32 v8, 0x8400, v7
	global_load_dwordx4 v[56:59], v8, s[8:9]
	v_add_u32_e32 v8, 0x8410, v7
	global_load_dwordx4 v[60:63], v8, s[8:9]
	v_add_u32_e32 v8, 0xb000, v7
	global_load_dwordx4 v[32:35], v8, s[8:9]
	v_add_u32_e32 v8, 0xb010, v7
	global_load_dwordx4 v[36:39], v8, s[8:9]
	v_add_u32_e32 v8, 0xdc00, v7
	global_load_dwordx4 v[64:67], v8, s[8:9]
	v_add_u32_e32 v8, 0xdc10, v7
	global_load_dwordx4 v[68:71], v8, s[8:9]
	global_load_dwordx4 v[40:43], v7, s[10:11] offset:0
	global_load_dwordx4 v[44:47], v7, s[10:11] offset:16
	v_add_u32_e32 v8, 0x2c00, v7
	global_load_dwordx4 v[72:75], v8, s[10:11]
	v_add_u32_e32 v8, 0x2c10, v7
	global_load_dwordx4 v[76:79], v8, s[10:11]
	v_lshlrev_b32_e32 v9, 1, v2
	v_mov_b64_e32 v[10:11], s[12:13]
	v_mad_u64_u32 v[10:11], s[2:3], v9, s90, v[10:11]
	v_mov_b32_e32 v12, v7
	v_mov_b32_e32 v13, 0
	v_lshl_add_u64 v[10:11], v[10:11], 0, v[12:13]
	global_load_dwordx4 v[80:83], v[10:11], off
	global_load_dwordx4 v[84:87], v[10:11], off offset:16
	v_add_co_u32_e32 v14, vcc, 0x2c00, v10
	v_addc_co_u32_e32 v15, vcc, 0, v11, vcc
	global_load_dwordx4 v[88:91], v[14:15], off
	global_load_dwordx4 v[92:95], v[14:15], off offset:16
	v_add_co_u32_e32 v14, vcc, 0x5800, v10
	v_addc_co_u32_e32 v15, vcc, 0, v11, vcc
	global_load_dwordx4 v[96:99], v[14:15], off
	global_load_dwordx4 v[100:103], v[14:15], off offset:16
	v_add_co_u32_e32 v14, vcc, 0x8400, v10
	v_addc_co_u32_e32 v15, vcc, 0, v11, vcc
	global_load_dwordx4 v[104:107], v[14:15], off
	global_load_dwordx4 v[108:111], v[14:15], off offset:16
	v_lshlrev_b32_e32 v9, 3, v2
	v_add_u32_e32 v9, 0x4000, v9
	v_mov_b64_e32 v[10:11], s[6:7]
	v_mad_u64_u32 v[10:11], s[2:3], v9, s91, v[10:11]
	v_mov_b32_e32 v12, v6
	v_mov_b32_e32 v13, 0
	v_lshl_add_u64 v[10:11], v[10:11], 0, v[12:13]
	global_load_dwordx4 v[112:115], v[10:11], off
	v_add_co_u32_e32 v14, vcc, 0x1600, v10
	v_addc_co_u32_e32 v15, vcc, 0, v11, vcc
	global_load_dwordx4 v[116:119], v[14:15], off
	v_add_co_u32_e32 v14, vcc, 0x2c00, v10
	v_addc_co_u32_e32 v15, vcc, 0, v11, vcc
	global_load_dwordx4 v[120:123], v[14:15], off
	v_add_co_u32_e32 v14, vcc, 0x4200, v10
	v_addc_co_u32_e32 v15, vcc, 0, v11, vcc
	global_load_dwordx4 v[124:127], v[14:15], off
	v_add_co_u32_e32 v14, vcc, 0x5800, v10
	v_addc_co_u32_e32 v15, vcc, 0, v11, vcc
	global_load_dwordx4 v[128:131], v[14:15], off
	v_add_co_u32_e32 v14, vcc, 0x6e00, v10
	v_addc_co_u32_e32 v15, vcc, 0, v11, vcc
	global_load_dwordx4 v[132:135], v[14:15], off
	v_add_co_u32_e32 v14, vcc, 0x8400, v10
	v_addc_co_u32_e32 v15, vcc, 0, v11, vcc
	global_load_dwordx4 v[136:139], v[14:15], off
	v_add_co_u32_e32 v14, vcc, 0x9a00, v10
	v_addc_co_u32_e32 v15, vcc, 0, v11, vcc
	global_load_dwordx4 v[140:143], v[14:15], off
	v_add_co_u32_e32 v14, vcc, 0xb000, v10
	v_addc_co_u32_e32 v15, vcc, 0, v11, vcc
	global_load_dwordx4 v[144:147], v[14:15], off
	v_add_co_u32_e32 v14, vcc, 0xc600, v10
	v_addc_co_u32_e32 v15, vcc, 0, v11, vcc
	global_load_dwordx4 v[148:151], v[14:15], off
	v_add_co_u32_e32 v14, vcc, 0xdc00, v10
	v_addc_co_u32_e32 v15, vcc, 0, v11, vcc
	global_load_dwordx4 v[152:155], v[14:15], off
	v_add_co_u32_e32 v14, vcc, 0xf200, v10
	v_addc_co_u32_e32 v15, vcc, 0, v11, vcc
	global_load_dwordx4 v[156:159], v[14:15], off
	v_add_co_u32_e32 v14, vcc, 0x10800, v10
	v_addc_co_u32_e32 v15, vcc, 0, v11, vcc
	global_load_dwordx4 v[160:163], v[14:15], off
	v_add_co_u32_e32 v14, vcc, 0x11e00, v10
	v_addc_co_u32_e32 v15, vcc, 0, v11, vcc
	global_load_dwordx4 v[164:167], v[14:15], off
	v_add_co_u32_e32 v14, vcc, 0x13400, v10
	v_addc_co_u32_e32 v15, vcc, 0, v11, vcc
	global_load_dwordx4 v[168:171], v[14:15], off
	v_add_co_u32_e32 v14, vcc, 0x14a00, v10
	v_addc_co_u32_e32 v15, vcc, 0, v11, vcc
	global_load_dwordx4 v[172:175], v[14:15], off
	v_mov_b64_e32 v[10:11], s[6:7]
	s_movk_i32 s2, 0x1600
	v_mad_u64_u32 v[10:11], s[16:17], v9, s2, v[10:11]
	v_lshl_add_u64 v[10:11], v[10:11], 0, v[12:13]
	s_mov_b32 s2, 0xbfb8aa3b
	s_mov_b32 s3, 0xbfb8aa3b
	s_waitcnt vmcnt(0)
	v_lshlrev_b32_e32 v176, 16, v112
	v_and_b32_e32 v177, 0xffff0000, v112
	v_lshlrev_b32_e32 v178, 16, v113
	v_and_b32_e32 v179, 0xffff0000, v113
	v_lshlrev_b32_e32 v180, 16, v114
	v_and_b32_e32 v181, 0xffff0000, v114
	v_lshlrev_b32_e32 v182, 16, v115
	v_and_b32_e32 v183, 0xffff0000, v115
	v_lshlrev_b32_e32 v184, 16, v116
	v_and_b32_e32 v185, 0xffff0000, v116
	v_lshlrev_b32_e32 v186, 16, v117
	v_and_b32_e32 v187, 0xffff0000, v117
	v_lshlrev_b32_e32 v188, 16, v118
	v_and_b32_e32 v189, 0xffff0000, v118
	v_lshlrev_b32_e32 v190, 16, v119
	v_and_b32_e32 v191, 0xffff0000, v119
	v_pk_fma_f32 v[80:81], v[80:81], v[16:17], v[40:41]
	v_pk_fma_f32 v[80:81], v[96:97], v[24:25], v[80:81]
	v_pk_fma_f32 v[80:81], v[176:177], v[32:33], v[80:81]
	v_pk_fma_f32 v[82:83], v[82:83], v[18:19], v[42:43]
	v_pk_fma_f32 v[82:83], v[98:99], v[26:27], v[82:83]
	v_pk_fma_f32 v[82:83], v[178:179], v[34:35], v[82:83]
	v_pk_fma_f32 v[84:85], v[84:85], v[20:21], v[44:45]
	v_pk_fma_f32 v[84:85], v[100:101], v[28:29], v[84:85]
	v_pk_fma_f32 v[84:85], v[180:181], v[36:37], v[84:85]
	v_pk_fma_f32 v[86:87], v[86:87], v[22:23], v[46:47]
	v_pk_fma_f32 v[86:87], v[102:103], v[30:31], v[86:87]
	v_pk_fma_f32 v[86:87], v[182:183], v[38:39], v[86:87]
	v_pk_fma_f32 v[88:89], v[88:89], v[48:49], v[72:73]
	v_pk_fma_f32 v[88:89], v[104:105], v[56:57], v[88:89]
	v_pk_fma_f32 v[88:89], v[184:185], v[64:65], v[88:89]
	v_pk_fma_f32 v[90:91], v[90:91], v[50:51], v[74:75]
	v_pk_fma_f32 v[90:91], v[106:107], v[58:59], v[90:91]
	v_pk_fma_f32 v[90:91], v[186:187], v[66:67], v[90:91]
	v_pk_fma_f32 v[92:93], v[92:93], v[52:53], v[76:77]
	v_pk_fma_f32 v[92:93], v[108:109], v[60:61], v[92:93]
	v_pk_fma_f32 v[92:93], v[188:189], v[68:69], v[92:93]
	v_pk_fma_f32 v[94:95], v[94:95], v[54:55], v[78:79]
	v_pk_fma_f32 v[94:95], v[110:111], v[62:63], v[94:95]
	v_pk_fma_f32 v[94:95], v[190:191], v[70:71], v[94:95]
	v_pk_mul_f32 v[224:225], v[80:81], s[2:3]
	v_exp_f32_e32 v224, v224
	v_exp_f32_e32 v225, v225
	s_nop 0
	v_pk_add_f32 v[224:225], v[224:225], 1.0 op_sel_hi:[1,0]
	v_rcp_f32_e32 v224, v224
	v_rcp_f32_e32 v225, v225
	s_nop 0
	v_pk_mul_f32 v[224:225], v[224:225], v[80:81]
	v_pk_mul_f32 v[224:225], v[224:225], v[88:89]
	v_cvt_pk_bf16_f32 v192, v224, v225
	v_pk_mul_f32 v[224:225], v[82:83], s[2:3]
	v_exp_f32_e32 v224, v224
	v_exp_f32_e32 v225, v225
	s_nop 0
	v_pk_add_f32 v[224:225], v[224:225], 1.0 op_sel_hi:[1,0]
	v_rcp_f32_e32 v224, v224
	v_rcp_f32_e32 v225, v225
	s_nop 0
	v_pk_mul_f32 v[224:225], v[224:225], v[82:83]
	v_pk_mul_f32 v[224:225], v[224:225], v[90:91]
	v_cvt_pk_bf16_f32 v193, v224, v225
	v_pk_mul_f32 v[224:225], v[84:85], s[2:3]
	v_exp_f32_e32 v224, v224
	v_exp_f32_e32 v225, v225
	s_nop 0
	v_pk_add_f32 v[224:225], v[224:225], 1.0 op_sel_hi:[1,0]
	v_rcp_f32_e32 v224, v224
	v_rcp_f32_e32 v225, v225
	s_nop 0
	v_pk_mul_f32 v[224:225], v[224:225], v[84:85]
	v_pk_mul_f32 v[224:225], v[224:225], v[92:93]
	v_cvt_pk_bf16_f32 v194, v224, v225
	v_pk_mul_f32 v[224:225], v[86:87], s[2:3]
	v_exp_f32_e32 v224, v224
	v_exp_f32_e32 v225, v225
	s_nop 0
	v_pk_add_f32 v[224:225], v[224:225], 1.0 op_sel_hi:[1,0]
	v_rcp_f32_e32 v224, v224
	v_rcp_f32_e32 v225, v225
	s_nop 0
	v_pk_mul_f32 v[224:225], v[224:225], v[86:87]
	v_pk_mul_f32 v[224:225], v[224:225], v[94:95]
	v_cvt_pk_bf16_f32 v195, v224, v225
	global_store_dwordx4 v[10:11], v[192:195], off
	v_lshlrev_b32_e32 v80, 16, v120
	v_and_b32_e32 v81, 0xffff0000, v120
	v_lshlrev_b32_e32 v82, 16, v121
	v_and_b32_e32 v83, 0xffff0000, v121
	v_lshlrev_b32_e32 v84, 16, v122
	v_and_b32_e32 v85, 0xffff0000, v122
	v_lshlrev_b32_e32 v86, 16, v123
	v_and_b32_e32 v87, 0xffff0000, v123
	v_lshlrev_b32_e32 v88, 16, v124
	v_and_b32_e32 v89, 0xffff0000, v124
	v_lshlrev_b32_e32 v90, 16, v125
	v_and_b32_e32 v91, 0xffff0000, v125
	v_lshlrev_b32_e32 v92, 16, v126
	v_and_b32_e32 v93, 0xffff0000, v126
	v_lshlrev_b32_e32 v94, 16, v127
	v_and_b32_e32 v95, 0xffff0000, v127
	v_pk_fma_f32 v[96:97], v[96:97], v[16:17], v[40:41]
	v_pk_fma_f32 v[96:97], v[176:177], v[24:25], v[96:97]
	v_pk_fma_f32 v[96:97], v[80:81], v[32:33], v[96:97]
	v_pk_fma_f32 v[98:99], v[98:99], v[18:19], v[42:43]
	v_pk_fma_f32 v[98:99], v[178:179], v[26:27], v[98:99]
	v_pk_fma_f32 v[98:99], v[82:83], v[34:35], v[98:99]
	v_pk_fma_f32 v[100:101], v[100:101], v[20:21], v[44:45]
	v_pk_fma_f32 v[100:101], v[180:181], v[28:29], v[100:101]
	v_pk_fma_f32 v[100:101], v[84:85], v[36:37], v[100:101]
	v_pk_fma_f32 v[102:103], v[102:103], v[22:23], v[46:47]
	v_pk_fma_f32 v[102:103], v[182:183], v[30:31], v[102:103]
	v_pk_fma_f32 v[102:103], v[86:87], v[38:39], v[102:103]
	v_pk_fma_f32 v[104:105], v[104:105], v[48:49], v[72:73]
	v_pk_fma_f32 v[104:105], v[184:185], v[56:57], v[104:105]
	v_pk_fma_f32 v[104:105], v[88:89], v[64:65], v[104:105]
	v_pk_fma_f32 v[106:107], v[106:107], v[50:51], v[74:75]
	v_pk_fma_f32 v[106:107], v[186:187], v[58:59], v[106:107]
	v_pk_fma_f32 v[106:107], v[90:91], v[66:67], v[106:107]
	v_pk_fma_f32 v[108:109], v[108:109], v[52:53], v[76:77]
	v_pk_fma_f32 v[108:109], v[188:189], v[60:61], v[108:109]
	v_pk_fma_f32 v[108:109], v[92:93], v[68:69], v[108:109]
	v_pk_fma_f32 v[110:111], v[110:111], v[54:55], v[78:79]
	v_pk_fma_f32 v[110:111], v[190:191], v[62:63], v[110:111]
	v_pk_fma_f32 v[110:111], v[94:95], v[70:71], v[110:111]
	v_pk_mul_f32 v[224:225], v[96:97], s[2:3]
	v_exp_f32_e32 v224, v224
	v_exp_f32_e32 v225, v225
	s_nop 0
	v_pk_add_f32 v[224:225], v[224:225], 1.0 op_sel_hi:[1,0]
	v_rcp_f32_e32 v224, v224
	v_rcp_f32_e32 v225, v225
	s_nop 0
	v_pk_mul_f32 v[224:225], v[224:225], v[96:97]
	v_pk_mul_f32 v[224:225], v[224:225], v[104:105]
	v_cvt_pk_bf16_f32 v196, v224, v225
	v_pk_mul_f32 v[224:225], v[98:99], s[2:3]
	v_exp_f32_e32 v224, v224
	v_exp_f32_e32 v225, v225
	s_nop 0
	v_pk_add_f32 v[224:225], v[224:225], 1.0 op_sel_hi:[1,0]
	v_rcp_f32_e32 v224, v224
	v_rcp_f32_e32 v225, v225
	s_nop 0
	v_pk_mul_f32 v[224:225], v[224:225], v[98:99]
	v_pk_mul_f32 v[224:225], v[224:225], v[106:107]
	v_cvt_pk_bf16_f32 v197, v224, v225
	v_pk_mul_f32 v[224:225], v[100:101], s[2:3]
	v_exp_f32_e32 v224, v224
	v_exp_f32_e32 v225, v225
	s_nop 0
	v_pk_add_f32 v[224:225], v[224:225], 1.0 op_sel_hi:[1,0]
	v_rcp_f32_e32 v224, v224
	v_rcp_f32_e32 v225, v225
	s_nop 0
	v_pk_mul_f32 v[224:225], v[224:225], v[100:101]
	v_pk_mul_f32 v[224:225], v[224:225], v[108:109]
	v_cvt_pk_bf16_f32 v198, v224, v225
	v_pk_mul_f32 v[224:225], v[102:103], s[2:3]
	v_exp_f32_e32 v224, v224
	v_exp_f32_e32 v225, v225
	s_nop 0
	v_pk_add_f32 v[224:225], v[224:225], 1.0 op_sel_hi:[1,0]
	v_rcp_f32_e32 v224, v224
	v_rcp_f32_e32 v225, v225
	s_nop 0
	v_pk_mul_f32 v[224:225], v[224:225], v[102:103]
	v_pk_mul_f32 v[224:225], v[224:225], v[110:111]
	v_cvt_pk_bf16_f32 v199, v224, v225
	v_add_co_u32_e32 v14, vcc, 0x1600, v10
	v_addc_co_u32_e32 v15, vcc, 0, v11, vcc
	global_store_dwordx4 v[14:15], v[196:199], off
	v_lshlrev_b32_e32 v96, 16, v128
	v_and_b32_e32 v97, 0xffff0000, v128
	v_lshlrev_b32_e32 v98, 16, v129
	v_and_b32_e32 v99, 0xffff0000, v129
	v_lshlrev_b32_e32 v100, 16, v130
	v_and_b32_e32 v101, 0xffff0000, v130
	v_lshlrev_b32_e32 v102, 16, v131
	v_and_b32_e32 v103, 0xffff0000, v131
	v_lshlrev_b32_e32 v104, 16, v132
	v_and_b32_e32 v105, 0xffff0000, v132
	v_lshlrev_b32_e32 v106, 16, v133
	v_and_b32_e32 v107, 0xffff0000, v133
	v_lshlrev_b32_e32 v108, 16, v134
	v_and_b32_e32 v109, 0xffff0000, v134
	v_lshlrev_b32_e32 v110, 16, v135
	v_and_b32_e32 v111, 0xffff0000, v135
	v_pk_fma_f32 v[176:177], v[176:177], v[16:17], v[40:41]
	v_pk_fma_f32 v[176:177], v[80:81], v[24:25], v[176:177]
	v_pk_fma_f32 v[176:177], v[96:97], v[32:33], v[176:177]
	v_pk_fma_f32 v[178:179], v[178:179], v[18:19], v[42:43]
	v_pk_fma_f32 v[178:179], v[82:83], v[26:27], v[178:179]
	v_pk_fma_f32 v[178:179], v[98:99], v[34:35], v[178:179]
	v_pk_fma_f32 v[180:181], v[180:181], v[20:21], v[44:45]
	v_pk_fma_f32 v[180:181], v[84:85], v[28:29], v[180:181]
	v_pk_fma_f32 v[180:181], v[100:101], v[36:37], v[180:181]
	v_pk_fma_f32 v[182:183], v[182:183], v[22:23], v[46:47]
	v_pk_fma_f32 v[182:183], v[86:87], v[30:31], v[182:183]
	v_pk_fma_f32 v[182:183], v[102:103], v[38:39], v[182:183]
	v_pk_fma_f32 v[184:185], v[184:185], v[48:49], v[72:73]
	v_pk_fma_f32 v[184:185], v[88:89], v[56:57], v[184:185]
	v_pk_fma_f32 v[184:185], v[104:105], v[64:65], v[184:185]
	v_pk_fma_f32 v[186:187], v[186:187], v[50:51], v[74:75]
	v_pk_fma_f32 v[186:187], v[90:91], v[58:59], v[186:187]
	v_pk_fma_f32 v[186:187], v[106:107], v[66:67], v[186:187]
	v_pk_fma_f32 v[188:189], v[188:189], v[52:53], v[76:77]
	v_pk_fma_f32 v[188:189], v[92:93], v[60:61], v[188:189]
	v_pk_fma_f32 v[188:189], v[108:109], v[68:69], v[188:189]
	v_pk_fma_f32 v[190:191], v[190:191], v[54:55], v[78:79]
	v_pk_fma_f32 v[190:191], v[94:95], v[62:63], v[190:191]
	v_pk_fma_f32 v[190:191], v[110:111], v[70:71], v[190:191]
	v_pk_mul_f32 v[224:225], v[176:177], s[2:3]
	v_exp_f32_e32 v224, v224
	v_exp_f32_e32 v225, v225
	s_nop 0
	v_pk_add_f32 v[224:225], v[224:225], 1.0 op_sel_hi:[1,0]
	v_rcp_f32_e32 v224, v224
	v_rcp_f32_e32 v225, v225
	s_nop 0
	v_pk_mul_f32 v[224:225], v[224:225], v[176:177]
	v_pk_mul_f32 v[224:225], v[224:225], v[184:185]
	v_cvt_pk_bf16_f32 v192, v224, v225
	v_pk_mul_f32 v[224:225], v[178:179], s[2:3]
	v_exp_f32_e32 v224, v224
	v_exp_f32_e32 v225, v225
	s_nop 0
	v_pk_add_f32 v[224:225], v[224:225], 1.0 op_sel_hi:[1,0]
	v_rcp_f32_e32 v224, v224
	v_rcp_f32_e32 v225, v225
	s_nop 0
	v_pk_mul_f32 v[224:225], v[224:225], v[178:179]
	v_pk_mul_f32 v[224:225], v[224:225], v[186:187]
	v_cvt_pk_bf16_f32 v193, v224, v225
	v_pk_mul_f32 v[224:225], v[180:181], s[2:3]
	v_exp_f32_e32 v224, v224
	v_exp_f32_e32 v225, v225
	s_nop 0
	v_pk_add_f32 v[224:225], v[224:225], 1.0 op_sel_hi:[1,0]
	v_rcp_f32_e32 v224, v224
	v_rcp_f32_e32 v225, v225
	s_nop 0
	v_pk_mul_f32 v[224:225], v[224:225], v[180:181]
	v_pk_mul_f32 v[224:225], v[224:225], v[188:189]
	v_cvt_pk_bf16_f32 v194, v224, v225
	v_pk_mul_f32 v[224:225], v[182:183], s[2:3]
	v_exp_f32_e32 v224, v224
	v_exp_f32_e32 v225, v225
	s_nop 0
	v_pk_add_f32 v[224:225], v[224:225], 1.0 op_sel_hi:[1,0]
	v_rcp_f32_e32 v224, v224
	v_rcp_f32_e32 v225, v225
	s_nop 0
	v_pk_mul_f32 v[224:225], v[224:225], v[182:183]
	v_pk_mul_f32 v[224:225], v[224:225], v[190:191]
	v_cvt_pk_bf16_f32 v195, v224, v225
	v_add_co_u32_e32 v14, vcc, 0x2c00, v10
	v_addc_co_u32_e32 v15, vcc, 0, v11, vcc
	global_store_dwordx4 v[14:15], v[192:195], off
	v_lshlrev_b32_e32 v176, 16, v136
	v_and_b32_e32 v177, 0xffff0000, v136
	v_lshlrev_b32_e32 v178, 16, v137
	v_and_b32_e32 v179, 0xffff0000, v137
	v_lshlrev_b32_e32 v180, 16, v138
	v_and_b32_e32 v181, 0xffff0000, v138
	v_lshlrev_b32_e32 v182, 16, v139
	v_and_b32_e32 v183, 0xffff0000, v139
	v_lshlrev_b32_e32 v184, 16, v140
	v_and_b32_e32 v185, 0xffff0000, v140
	v_lshlrev_b32_e32 v186, 16, v141
	v_and_b32_e32 v187, 0xffff0000, v141
	v_lshlrev_b32_e32 v188, 16, v142
	v_and_b32_e32 v189, 0xffff0000, v142
	v_lshlrev_b32_e32 v190, 16, v143
	v_and_b32_e32 v191, 0xffff0000, v143
	v_pk_fma_f32 v[80:81], v[80:81], v[16:17], v[40:41]
	v_pk_fma_f32 v[80:81], v[96:97], v[24:25], v[80:81]
	v_pk_fma_f32 v[80:81], v[176:177], v[32:33], v[80:81]
	v_pk_fma_f32 v[82:83], v[82:83], v[18:19], v[42:43]
	v_pk_fma_f32 v[82:83], v[98:99], v[26:27], v[82:83]
	v_pk_fma_f32 v[82:83], v[178:179], v[34:35], v[82:83]
	v_pk_fma_f32 v[84:85], v[84:85], v[20:21], v[44:45]
	v_pk_fma_f32 v[84:85], v[100:101], v[28:29], v[84:85]
	v_pk_fma_f32 v[84:85], v[180:181], v[36:37], v[84:85]
	v_pk_fma_f32 v[86:87], v[86:87], v[22:23], v[46:47]
	v_pk_fma_f32 v[86:87], v[102:103], v[30:31], v[86:87]
	v_pk_fma_f32 v[86:87], v[182:183], v[38:39], v[86:87]
	v_pk_fma_f32 v[88:89], v[88:89], v[48:49], v[72:73]
	v_pk_fma_f32 v[88:89], v[104:105], v[56:57], v[88:89]
	v_pk_fma_f32 v[88:89], v[184:185], v[64:65], v[88:89]
	v_pk_fma_f32 v[90:91], v[90:91], v[50:51], v[74:75]
	v_pk_fma_f32 v[90:91], v[106:107], v[58:59], v[90:91]
	v_pk_fma_f32 v[90:91], v[186:187], v[66:67], v[90:91]
	v_pk_fma_f32 v[92:93], v[92:93], v[52:53], v[76:77]
	v_pk_fma_f32 v[92:93], v[108:109], v[60:61], v[92:93]
	v_pk_fma_f32 v[92:93], v[188:189], v[68:69], v[92:93]
	v_pk_fma_f32 v[94:95], v[94:95], v[54:55], v[78:79]
	v_pk_fma_f32 v[94:95], v[110:111], v[62:63], v[94:95]
	v_pk_fma_f32 v[94:95], v[190:191], v[70:71], v[94:95]
	v_pk_mul_f32 v[224:225], v[80:81], s[2:3]
	v_exp_f32_e32 v224, v224
	v_exp_f32_e32 v225, v225
	s_nop 0
	v_pk_add_f32 v[224:225], v[224:225], 1.0 op_sel_hi:[1,0]
	v_rcp_f32_e32 v224, v224
	v_rcp_f32_e32 v225, v225
	s_nop 0
	v_pk_mul_f32 v[224:225], v[224:225], v[80:81]
	v_pk_mul_f32 v[224:225], v[224:225], v[88:89]
	v_cvt_pk_bf16_f32 v196, v224, v225
	v_pk_mul_f32 v[224:225], v[82:83], s[2:3]
	v_exp_f32_e32 v224, v224
	v_exp_f32_e32 v225, v225
	s_nop 0
	v_pk_add_f32 v[224:225], v[224:225], 1.0 op_sel_hi:[1,0]
	v_rcp_f32_e32 v224, v224
	v_rcp_f32_e32 v225, v225
	s_nop 0
	v_pk_mul_f32 v[224:225], v[224:225], v[82:83]
	v_pk_mul_f32 v[224:225], v[224:225], v[90:91]
	v_cvt_pk_bf16_f32 v197, v224, v225
	v_pk_mul_f32 v[224:225], v[84:85], s[2:3]
	v_exp_f32_e32 v224, v224
	v_exp_f32_e32 v225, v225
	s_nop 0
	v_pk_add_f32 v[224:225], v[224:225], 1.0 op_sel_hi:[1,0]
	v_rcp_f32_e32 v224, v224
	v_rcp_f32_e32 v225, v225
	s_nop 0
	v_pk_mul_f32 v[224:225], v[224:225], v[84:85]
	v_pk_mul_f32 v[224:225], v[224:225], v[92:93]
	v_cvt_pk_bf16_f32 v198, v224, v225
	v_pk_mul_f32 v[224:225], v[86:87], s[2:3]
	v_exp_f32_e32 v224, v224
	v_exp_f32_e32 v225, v225
	s_nop 0
	v_pk_add_f32 v[224:225], v[224:225], 1.0 op_sel_hi:[1,0]
	v_rcp_f32_e32 v224, v224
	v_rcp_f32_e32 v225, v225
	s_nop 0
	v_pk_mul_f32 v[224:225], v[224:225], v[86:87]
	v_pk_mul_f32 v[224:225], v[224:225], v[94:95]
	v_cvt_pk_bf16_f32 v199, v224, v225
	v_add_co_u32_e32 v14, vcc, 0x4200, v10
	v_addc_co_u32_e32 v15, vcc, 0, v11, vcc
	global_store_dwordx4 v[14:15], v[196:199], off
	v_lshlrev_b32_e32 v80, 16, v144
	v_and_b32_e32 v81, 0xffff0000, v144
	v_lshlrev_b32_e32 v82, 16, v145
	v_and_b32_e32 v83, 0xffff0000, v145
	v_lshlrev_b32_e32 v84, 16, v146
	v_and_b32_e32 v85, 0xffff0000, v146
	v_lshlrev_b32_e32 v86, 16, v147
	v_and_b32_e32 v87, 0xffff0000, v147
	v_lshlrev_b32_e32 v88, 16, v148
	v_and_b32_e32 v89, 0xffff0000, v148
	v_lshlrev_b32_e32 v90, 16, v149
	v_and_b32_e32 v91, 0xffff0000, v149
	v_lshlrev_b32_e32 v92, 16, v150
	v_and_b32_e32 v93, 0xffff0000, v150
	v_lshlrev_b32_e32 v94, 16, v151
	v_and_b32_e32 v95, 0xffff0000, v151
	v_pk_fma_f32 v[96:97], v[96:97], v[16:17], v[40:41]
	v_pk_fma_f32 v[96:97], v[176:177], v[24:25], v[96:97]
	v_pk_fma_f32 v[96:97], v[80:81], v[32:33], v[96:97]
	v_pk_fma_f32 v[98:99], v[98:99], v[18:19], v[42:43]
	v_pk_fma_f32 v[98:99], v[178:179], v[26:27], v[98:99]
	v_pk_fma_f32 v[98:99], v[82:83], v[34:35], v[98:99]
	v_pk_fma_f32 v[100:101], v[100:101], v[20:21], v[44:45]
	v_pk_fma_f32 v[100:101], v[180:181], v[28:29], v[100:101]
	v_pk_fma_f32 v[100:101], v[84:85], v[36:37], v[100:101]
	v_pk_fma_f32 v[102:103], v[102:103], v[22:23], v[46:47]
	v_pk_fma_f32 v[102:103], v[182:183], v[30:31], v[102:103]
	v_pk_fma_f32 v[102:103], v[86:87], v[38:39], v[102:103]
	v_pk_fma_f32 v[104:105], v[104:105], v[48:49], v[72:73]
	v_pk_fma_f32 v[104:105], v[184:185], v[56:57], v[104:105]
	v_pk_fma_f32 v[104:105], v[88:89], v[64:65], v[104:105]
	v_pk_fma_f32 v[106:107], v[106:107], v[50:51], v[74:75]
	v_pk_fma_f32 v[106:107], v[186:187], v[58:59], v[106:107]
	v_pk_fma_f32 v[106:107], v[90:91], v[66:67], v[106:107]
	v_pk_fma_f32 v[108:109], v[108:109], v[52:53], v[76:77]
	v_pk_fma_f32 v[108:109], v[188:189], v[60:61], v[108:109]
	v_pk_fma_f32 v[108:109], v[92:93], v[68:69], v[108:109]
	v_pk_fma_f32 v[110:111], v[110:111], v[54:55], v[78:79]
	v_pk_fma_f32 v[110:111], v[190:191], v[62:63], v[110:111]
	v_pk_fma_f32 v[110:111], v[94:95], v[70:71], v[110:111]
	v_pk_mul_f32 v[224:225], v[96:97], s[2:3]
	v_exp_f32_e32 v224, v224
	v_exp_f32_e32 v225, v225
	s_nop 0
	v_pk_add_f32 v[224:225], v[224:225], 1.0 op_sel_hi:[1,0]
	v_rcp_f32_e32 v224, v224
	v_rcp_f32_e32 v225, v225
	s_nop 0
	v_pk_mul_f32 v[224:225], v[224:225], v[96:97]
	v_pk_mul_f32 v[224:225], v[224:225], v[104:105]
	v_cvt_pk_bf16_f32 v192, v224, v225
	v_pk_mul_f32 v[224:225], v[98:99], s[2:3]
	v_exp_f32_e32 v224, v224
	v_exp_f32_e32 v225, v225
	s_nop 0
	v_pk_add_f32 v[224:225], v[224:225], 1.0 op_sel_hi:[1,0]
	v_rcp_f32_e32 v224, v224
	v_rcp_f32_e32 v225, v225
	s_nop 0
	v_pk_mul_f32 v[224:225], v[224:225], v[98:99]
	v_pk_mul_f32 v[224:225], v[224:225], v[106:107]
	v_cvt_pk_bf16_f32 v193, v224, v225
	v_pk_mul_f32 v[224:225], v[100:101], s[2:3]
	v_exp_f32_e32 v224, v224
	v_exp_f32_e32 v225, v225
	s_nop 0
	v_pk_add_f32 v[224:225], v[224:225], 1.0 op_sel_hi:[1,0]
	v_rcp_f32_e32 v224, v224
	v_rcp_f32_e32 v225, v225
	s_nop 0
	v_pk_mul_f32 v[224:225], v[224:225], v[100:101]
	v_pk_mul_f32 v[224:225], v[224:225], v[108:109]
	v_cvt_pk_bf16_f32 v194, v224, v225
	v_pk_mul_f32 v[224:225], v[102:103], s[2:3]
	v_exp_f32_e32 v224, v224
	v_exp_f32_e32 v225, v225
	s_nop 0
	v_pk_add_f32 v[224:225], v[224:225], 1.0 op_sel_hi:[1,0]
	v_rcp_f32_e32 v224, v224
	v_rcp_f32_e32 v225, v225
	s_nop 0
	v_pk_mul_f32 v[224:225], v[224:225], v[102:103]
	v_pk_mul_f32 v[224:225], v[224:225], v[110:111]
	v_cvt_pk_bf16_f32 v195, v224, v225
	v_add_co_u32_e32 v14, vcc, 0x5800, v10
	v_addc_co_u32_e32 v15, vcc, 0, v11, vcc
	global_store_dwordx4 v[14:15], v[192:195], off
	v_lshlrev_b32_e32 v96, 16, v152
	v_and_b32_e32 v97, 0xffff0000, v152
	v_lshlrev_b32_e32 v98, 16, v153
	v_and_b32_e32 v99, 0xffff0000, v153
	v_lshlrev_b32_e32 v100, 16, v154
	v_and_b32_e32 v101, 0xffff0000, v154
	v_lshlrev_b32_e32 v102, 16, v155
	v_and_b32_e32 v103, 0xffff0000, v155
	v_lshlrev_b32_e32 v104, 16, v156
	v_and_b32_e32 v105, 0xffff0000, v156
	v_lshlrev_b32_e32 v106, 16, v157
	v_and_b32_e32 v107, 0xffff0000, v157
	v_lshlrev_b32_e32 v108, 16, v158
	v_and_b32_e32 v109, 0xffff0000, v158
	v_lshlrev_b32_e32 v110, 16, v159
	v_and_b32_e32 v111, 0xffff0000, v159
	v_pk_fma_f32 v[176:177], v[176:177], v[16:17], v[40:41]
	v_pk_fma_f32 v[176:177], v[80:81], v[24:25], v[176:177]
	v_pk_fma_f32 v[176:177], v[96:97], v[32:33], v[176:177]
	v_pk_fma_f32 v[178:179], v[178:179], v[18:19], v[42:43]
	v_pk_fma_f32 v[178:179], v[82:83], v[26:27], v[178:179]
	v_pk_fma_f32 v[178:179], v[98:99], v[34:35], v[178:179]
	v_pk_fma_f32 v[180:181], v[180:181], v[20:21], v[44:45]
	v_pk_fma_f32 v[180:181], v[84:85], v[28:29], v[180:181]
	v_pk_fma_f32 v[180:181], v[100:101], v[36:37], v[180:181]
	v_pk_fma_f32 v[182:183], v[182:183], v[22:23], v[46:47]
	v_pk_fma_f32 v[182:183], v[86:87], v[30:31], v[182:183]
	v_pk_fma_f32 v[182:183], v[102:103], v[38:39], v[182:183]
	v_pk_fma_f32 v[184:185], v[184:185], v[48:49], v[72:73]
	v_pk_fma_f32 v[184:185], v[88:89], v[56:57], v[184:185]
	v_pk_fma_f32 v[184:185], v[104:105], v[64:65], v[184:185]
	v_pk_fma_f32 v[186:187], v[186:187], v[50:51], v[74:75]
	v_pk_fma_f32 v[186:187], v[90:91], v[58:59], v[186:187]
	v_pk_fma_f32 v[186:187], v[106:107], v[66:67], v[186:187]
	v_pk_fma_f32 v[188:189], v[188:189], v[52:53], v[76:77]
	v_pk_fma_f32 v[188:189], v[92:93], v[60:61], v[188:189]
	v_pk_fma_f32 v[188:189], v[108:109], v[68:69], v[188:189]
	v_pk_fma_f32 v[190:191], v[190:191], v[54:55], v[78:79]
	v_pk_fma_f32 v[190:191], v[94:95], v[62:63], v[190:191]
	v_pk_fma_f32 v[190:191], v[110:111], v[70:71], v[190:191]
	v_pk_mul_f32 v[224:225], v[176:177], s[2:3]
	v_exp_f32_e32 v224, v224
	v_exp_f32_e32 v225, v225
	s_nop 0
	v_pk_add_f32 v[224:225], v[224:225], 1.0 op_sel_hi:[1,0]
	v_rcp_f32_e32 v224, v224
	v_rcp_f32_e32 v225, v225
	s_nop 0
	v_pk_mul_f32 v[224:225], v[224:225], v[176:177]
	v_pk_mul_f32 v[224:225], v[224:225], v[184:185]
	v_cvt_pk_bf16_f32 v196, v224, v225
	v_pk_mul_f32 v[224:225], v[178:179], s[2:3]
	v_exp_f32_e32 v224, v224
	v_exp_f32_e32 v225, v225
	s_nop 0
	v_pk_add_f32 v[224:225], v[224:225], 1.0 op_sel_hi:[1,0]
	v_rcp_f32_e32 v224, v224
	v_rcp_f32_e32 v225, v225
	s_nop 0
	v_pk_mul_f32 v[224:225], v[224:225], v[178:179]
	v_pk_mul_f32 v[224:225], v[224:225], v[186:187]
	v_cvt_pk_bf16_f32 v197, v224, v225
	v_pk_mul_f32 v[224:225], v[180:181], s[2:3]
	v_exp_f32_e32 v224, v224
	v_exp_f32_e32 v225, v225
	s_nop 0
	v_pk_add_f32 v[224:225], v[224:225], 1.0 op_sel_hi:[1,0]
	v_rcp_f32_e32 v224, v224
	v_rcp_f32_e32 v225, v225
	s_nop 0
	v_pk_mul_f32 v[224:225], v[224:225], v[180:181]
	v_pk_mul_f32 v[224:225], v[224:225], v[188:189]
	v_cvt_pk_bf16_f32 v198, v224, v225
	v_pk_mul_f32 v[224:225], v[182:183], s[2:3]
	v_exp_f32_e32 v224, v224
	v_exp_f32_e32 v225, v225
	s_nop 0
	v_pk_add_f32 v[224:225], v[224:225], 1.0 op_sel_hi:[1,0]
	v_rcp_f32_e32 v224, v224
	v_rcp_f32_e32 v225, v225
	s_nop 0
	v_pk_mul_f32 v[224:225], v[224:225], v[182:183]
	v_pk_mul_f32 v[224:225], v[224:225], v[190:191]
	v_cvt_pk_bf16_f32 v199, v224, v225
	v_add_co_u32_e32 v14, vcc, 0x6e00, v10
	v_addc_co_u32_e32 v15, vcc, 0, v11, vcc
	global_store_dwordx4 v[14:15], v[196:199], off
	v_lshlrev_b32_e32 v176, 16, v160
	v_and_b32_e32 v177, 0xffff0000, v160
	v_lshlrev_b32_e32 v178, 16, v161
	v_and_b32_e32 v179, 0xffff0000, v161
	v_lshlrev_b32_e32 v180, 16, v162
	v_and_b32_e32 v181, 0xffff0000, v162
	v_lshlrev_b32_e32 v182, 16, v163
	v_and_b32_e32 v183, 0xffff0000, v163
	v_lshlrev_b32_e32 v184, 16, v164
	v_and_b32_e32 v185, 0xffff0000, v164
	v_lshlrev_b32_e32 v186, 16, v165
	v_and_b32_e32 v187, 0xffff0000, v165
	v_lshlrev_b32_e32 v188, 16, v166
	v_and_b32_e32 v189, 0xffff0000, v166
	v_lshlrev_b32_e32 v190, 16, v167
	v_and_b32_e32 v191, 0xffff0000, v167
	v_pk_fma_f32 v[80:81], v[80:81], v[16:17], v[40:41]
	v_pk_fma_f32 v[80:81], v[96:97], v[24:25], v[80:81]
	v_pk_fma_f32 v[80:81], v[176:177], v[32:33], v[80:81]
	v_pk_fma_f32 v[82:83], v[82:83], v[18:19], v[42:43]
	v_pk_fma_f32 v[82:83], v[98:99], v[26:27], v[82:83]
	v_pk_fma_f32 v[82:83], v[178:179], v[34:35], v[82:83]
	v_pk_fma_f32 v[84:85], v[84:85], v[20:21], v[44:45]
	v_pk_fma_f32 v[84:85], v[100:101], v[28:29], v[84:85]
	v_pk_fma_f32 v[84:85], v[180:181], v[36:37], v[84:85]
	v_pk_fma_f32 v[86:87], v[86:87], v[22:23], v[46:47]
	v_pk_fma_f32 v[86:87], v[102:103], v[30:31], v[86:87]
	v_pk_fma_f32 v[86:87], v[182:183], v[38:39], v[86:87]
	v_pk_fma_f32 v[88:89], v[88:89], v[48:49], v[72:73]
	v_pk_fma_f32 v[88:89], v[104:105], v[56:57], v[88:89]
	v_pk_fma_f32 v[88:89], v[184:185], v[64:65], v[88:89]
	v_pk_fma_f32 v[90:91], v[90:91], v[50:51], v[74:75]
	v_pk_fma_f32 v[90:91], v[106:107], v[58:59], v[90:91]
	v_pk_fma_f32 v[90:91], v[186:187], v[66:67], v[90:91]
	v_pk_fma_f32 v[92:93], v[92:93], v[52:53], v[76:77]
	v_pk_fma_f32 v[92:93], v[108:109], v[60:61], v[92:93]
	v_pk_fma_f32 v[92:93], v[188:189], v[68:69], v[92:93]
	v_pk_fma_f32 v[94:95], v[94:95], v[54:55], v[78:79]
	v_pk_fma_f32 v[94:95], v[110:111], v[62:63], v[94:95]
	v_pk_fma_f32 v[94:95], v[190:191], v[70:71], v[94:95]
	v_pk_mul_f32 v[224:225], v[80:81], s[2:3]
	v_exp_f32_e32 v224, v224
	v_exp_f32_e32 v225, v225
	s_nop 0
	v_pk_add_f32 v[224:225], v[224:225], 1.0 op_sel_hi:[1,0]
	v_rcp_f32_e32 v224, v224
	v_rcp_f32_e32 v225, v225
	s_nop 0
	v_pk_mul_f32 v[224:225], v[224:225], v[80:81]
	v_pk_mul_f32 v[224:225], v[224:225], v[88:89]
	v_cvt_pk_bf16_f32 v192, v224, v225
	v_pk_mul_f32 v[224:225], v[82:83], s[2:3]
	v_exp_f32_e32 v224, v224
	v_exp_f32_e32 v225, v225
	s_nop 0
	v_pk_add_f32 v[224:225], v[224:225], 1.0 op_sel_hi:[1,0]
	v_rcp_f32_e32 v224, v224
	v_rcp_f32_e32 v225, v225
	s_nop 0
	v_pk_mul_f32 v[224:225], v[224:225], v[82:83]
	v_pk_mul_f32 v[224:225], v[224:225], v[90:91]
	v_cvt_pk_bf16_f32 v193, v224, v225
	v_pk_mul_f32 v[224:225], v[84:85], s[2:3]
	v_exp_f32_e32 v224, v224
	v_exp_f32_e32 v225, v225
	s_nop 0
	v_pk_add_f32 v[224:225], v[224:225], 1.0 op_sel_hi:[1,0]
	v_rcp_f32_e32 v224, v224
	v_rcp_f32_e32 v225, v225
	s_nop 0
	v_pk_mul_f32 v[224:225], v[224:225], v[84:85]
	v_pk_mul_f32 v[224:225], v[224:225], v[92:93]
	v_cvt_pk_bf16_f32 v194, v224, v225
	v_pk_mul_f32 v[224:225], v[86:87], s[2:3]
	v_exp_f32_e32 v224, v224
	v_exp_f32_e32 v225, v225
	s_nop 0
	v_pk_add_f32 v[224:225], v[224:225], 1.0 op_sel_hi:[1,0]
	v_rcp_f32_e32 v224, v224
	v_rcp_f32_e32 v225, v225
	s_nop 0
	v_pk_mul_f32 v[224:225], v[224:225], v[86:87]
	v_pk_mul_f32 v[224:225], v[224:225], v[94:95]
	v_cvt_pk_bf16_f32 v195, v224, v225
	v_add_co_u32_e32 v14, vcc, 0x8400, v10
	v_addc_co_u32_e32 v15, vcc, 0, v11, vcc
	global_store_dwordx4 v[14:15], v[192:195], off
	v_lshlrev_b32_e32 v80, 16, v168
	v_and_b32_e32 v81, 0xffff0000, v168
	v_lshlrev_b32_e32 v82, 16, v169
	v_and_b32_e32 v83, 0xffff0000, v169
	v_lshlrev_b32_e32 v84, 16, v170
	v_and_b32_e32 v85, 0xffff0000, v170
	v_lshlrev_b32_e32 v86, 16, v171
	v_and_b32_e32 v87, 0xffff0000, v171
	v_lshlrev_b32_e32 v88, 16, v172
	v_and_b32_e32 v89, 0xffff0000, v172
	v_lshlrev_b32_e32 v90, 16, v173
	v_and_b32_e32 v91, 0xffff0000, v173
	v_lshlrev_b32_e32 v92, 16, v174
	v_and_b32_e32 v93, 0xffff0000, v174
	v_lshlrev_b32_e32 v94, 16, v175
	v_and_b32_e32 v95, 0xffff0000, v175
	v_pk_fma_f32 v[96:97], v[96:97], v[16:17], v[40:41]
	v_pk_fma_f32 v[96:97], v[176:177], v[24:25], v[96:97]
	v_pk_fma_f32 v[96:97], v[80:81], v[32:33], v[96:97]
	v_pk_fma_f32 v[98:99], v[98:99], v[18:19], v[42:43]
	v_pk_fma_f32 v[98:99], v[178:179], v[26:27], v[98:99]
	v_pk_fma_f32 v[98:99], v[82:83], v[34:35], v[98:99]
	v_pk_fma_f32 v[100:101], v[100:101], v[20:21], v[44:45]
	v_pk_fma_f32 v[100:101], v[180:181], v[28:29], v[100:101]
	v_pk_fma_f32 v[100:101], v[84:85], v[36:37], v[100:101]
	v_pk_fma_f32 v[102:103], v[102:103], v[22:23], v[46:47]
	v_pk_fma_f32 v[102:103], v[182:183], v[30:31], v[102:103]
	v_pk_fma_f32 v[102:103], v[86:87], v[38:39], v[102:103]
	v_pk_fma_f32 v[104:105], v[104:105], v[48:49], v[72:73]
	v_pk_fma_f32 v[104:105], v[184:185], v[56:57], v[104:105]
	v_pk_fma_f32 v[104:105], v[88:89], v[64:65], v[104:105]
	v_pk_fma_f32 v[106:107], v[106:107], v[50:51], v[74:75]
	v_pk_fma_f32 v[106:107], v[186:187], v[58:59], v[106:107]
	v_pk_fma_f32 v[106:107], v[90:91], v[66:67], v[106:107]
	v_pk_fma_f32 v[108:109], v[108:109], v[52:53], v[76:77]
	v_pk_fma_f32 v[108:109], v[188:189], v[60:61], v[108:109]
	v_pk_fma_f32 v[108:109], v[92:93], v[68:69], v[108:109]
	v_pk_fma_f32 v[110:111], v[110:111], v[54:55], v[78:79]
	v_pk_fma_f32 v[110:111], v[190:191], v[62:63], v[110:111]
	v_pk_fma_f32 v[110:111], v[94:95], v[70:71], v[110:111]
	v_pk_mul_f32 v[224:225], v[96:97], s[2:3]
	v_exp_f32_e32 v224, v224
	v_exp_f32_e32 v225, v225
	s_nop 0
	v_pk_add_f32 v[224:225], v[224:225], 1.0 op_sel_hi:[1,0]
	v_rcp_f32_e32 v224, v224
	v_rcp_f32_e32 v225, v225
	s_nop 0
	v_pk_mul_f32 v[224:225], v[224:225], v[96:97]
	v_pk_mul_f32 v[224:225], v[224:225], v[104:105]
	v_cvt_pk_bf16_f32 v196, v224, v225
	v_pk_mul_f32 v[224:225], v[98:99], s[2:3]
	v_exp_f32_e32 v224, v224
	v_exp_f32_e32 v225, v225
	s_nop 0
	v_pk_add_f32 v[224:225], v[224:225], 1.0 op_sel_hi:[1,0]
	v_rcp_f32_e32 v224, v224
	v_rcp_f32_e32 v225, v225
	s_nop 0
	v_pk_mul_f32 v[224:225], v[224:225], v[98:99]
	v_pk_mul_f32 v[224:225], v[224:225], v[106:107]
	v_cvt_pk_bf16_f32 v197, v224, v225
	v_pk_mul_f32 v[224:225], v[100:101], s[2:3]
	v_exp_f32_e32 v224, v224
	v_exp_f32_e32 v225, v225
	s_nop 0
	v_pk_add_f32 v[224:225], v[224:225], 1.0 op_sel_hi:[1,0]
	v_rcp_f32_e32 v224, v224
	v_rcp_f32_e32 v225, v225
	s_nop 0
	v_pk_mul_f32 v[224:225], v[224:225], v[100:101]
	v_pk_mul_f32 v[224:225], v[224:225], v[108:109]
	v_cvt_pk_bf16_f32 v198, v224, v225
	v_pk_mul_f32 v[224:225], v[102:103], s[2:3]
	v_exp_f32_e32 v224, v224
	v_exp_f32_e32 v225, v225
	s_nop 0
	v_pk_add_f32 v[224:225], v[224:225], 1.0 op_sel_hi:[1,0]
	v_rcp_f32_e32 v224, v224
	v_rcp_f32_e32 v225, v225
	s_nop 0
	v_pk_mul_f32 v[224:225], v[224:225], v[102:103]
	v_pk_mul_f32 v[224:225], v[224:225], v[110:111]
	v_cvt_pk_bf16_f32 v199, v224, v225
	v_add_co_u32_e32 v14, vcc, 0x9a00, v10
	v_addc_co_u32_e32 v15, vcc, 0, v11, vcc
	global_store_dwordx4 v[14:15], v[196:199], off
	s_branch .LBB0_193
